# strategy 7: SwiGLU epilogue row pointers computed by one 64-bit constant add from the first row pointer instead of a 64-bit mad + add per row group; plus gate-epilogue clamp; on k-inner Gray MFMA orde
# baseline (speedup 1.0000x reference)
.LBB0_118:
	s_lshl_b32 s49, s49, 10
	s_and_b32 s49, s49, 0x400
	v_add_u32_e32 v151, s49, v141
	ds_read_b32 v154, v151
	v_mul_f32_e32 v114, v122, v114
	v_mul_f32_e32 v118, v126, v118
	v_mul_f32_e32 v119, v127, v119
	v_mul_f32_e32 v115, v123, v115
	s_waitcnt lgkmcnt(0)
	v_mul_f32_e32 v155, 0xbfb8aa3b, v154
	v_mul_f32_e32 v154, v154, v154
	v_mul_f32_e32 v156, v126, v155
	v_mul_f32_e32 v157, v122, v155
	v_mul_f32_e32 v158, v127, v155
	v_mul_f32_e32 v159, v123, v155
	v_mul_f32_e32 v160, v128, v155
	v_mul_f32_e32 v161, v124, v155
	v_mul_f32_e32 v162, v129, v155
	v_mul_f32_e32 v155, v125, v155
	v_exp_f32_e32 v156, v156
	v_exp_f32_e32 v158, v158
	v_exp_f32_e32 v160, v160
	v_exp_f32_e32 v162, v162
	v_exp_f32_e32 v157, v157
	v_exp_f32_e32 v159, v159
	v_exp_f32_e32 v161, v161
	v_exp_f32_e32 v155, v155
	v_rcp_f32_e32 v122, v154
	v_mul_f32_e32 v120, v128, v120
	v_mul_f32_e32 v116, v124, v116
	v_mul_f32_e32 v121, v129, v121
	v_mul_f32_e32 v117, v125, v117
	v_fma_f32 v123, v156, v122, v122
	v_fma_f32 v124, v158, v122, v122
	v_fma_f32 v125, v160, v122, v122
	v_fma_f32 v126, v162, v122, v122
	v_fma_f32 v127, v157, v122, v122
	v_fma_f32 v128, v159, v122, v122
	v_fma_f32 v129, v161, v122, v122
	v_fmac_f32_e32 v122, v155, v122
	v_rcp_f32_e32 v123, v123
	v_rcp_f32_e32 v122, v122
	v_rcp_f32_e32 v124, v124
	v_rcp_f32_e32 v125, v125
	v_rcp_f32_e32 v126, v126
	v_rcp_f32_e32 v127, v127
	v_rcp_f32_e32 v128, v128
	v_rcp_f32_e32 v129, v129
	v_mul_f32_e32 v118, v118, v123
	v_mul_f32_e32 v117, v117, v122
	v_mul_f32_e32 v119, v119, v124
	v_mul_f32_e32 v120, v120, v125
	v_mul_f32_e32 v121, v121, v126
	v_mul_f32_e32 v123, v114, v127
	v_mul_f32_e32 v124, v115, v128
	v_mul_f32_e32 v125, v116, v129
	v_cvt_pk_bf16_f32 v114, v118, v119
	v_cvt_pk_bf16_f32 v115, v120, v121
	v_cvt_pk_bf16_f32 v116, v123, v124
	v_cvt_pk_bf16_f32 v117, v125, v117
	ds_read_b32 v118, v151 offset:64
	v_lshl_or_b32 v134, s21, 7, v142
	v_lshl_add_u32 v150, s24, 8, v140
	v_ashrrev_i32_e32 v135, 31, v134
	v_mov_b64_e32 v[132:133], s[0:1]
	s_movk_i32 s21, 0x2c00
	v_mad_i64_i32 v[152:153], s[50:51], v150, s21, v[132:133]
	v_lshlrev_b64 v[134:135], 1, v[134:135]
	v_lshl_add_u64 v[152:153], v[152:153], 0, v[134:135]
	global_store_dwordx4 v[152:153], v[114:117], off
	v_mul_f32_e32 v98, v106, v98
	v_mul_f32_e32 v102, v110, v102
	s_waitcnt lgkmcnt(0)
	v_mul_f32_e32 v116, 0xbfb8aa3b, v118
	v_mul_f32_e32 v117, v118, v118
	v_mul_f32_e32 v118, v110, v116
	v_mul_f32_e32 v119, v106, v116
	v_mul_f32_e32 v120, v111, v116
	v_mul_f32_e32 v121, v107, v116
	v_mul_f32_e32 v122, v112, v116
	v_mul_f32_e32 v123, v108, v116
	v_mul_f32_e32 v124, v113, v116
	v_mul_f32_e32 v116, v109, v116
	v_exp_f32_e32 v118, v118
	v_exp_f32_e32 v120, v120
	v_exp_f32_e32 v122, v122
	v_exp_f32_e32 v124, v124
	v_exp_f32_e32 v119, v119
	v_exp_f32_e32 v121, v121
	v_exp_f32_e32 v123, v123
	v_exp_f32_e32 v116, v116
	v_rcp_f32_e32 v106, v117
	v_mul_f32_e32 v103, v111, v103
	v_mul_f32_e32 v99, v107, v99
	v_mul_f32_e32 v104, v112, v104
	v_mul_f32_e32 v100, v108, v100
	v_mul_f32_e32 v105, v113, v105
	v_mul_f32_e32 v101, v109, v101
	v_fma_f32 v107, v118, v106, v106
	v_fma_f32 v108, v120, v106, v106
	v_fma_f32 v109, v122, v106, v106
	v_fma_f32 v110, v124, v106, v106
	v_fma_f32 v111, v119, v106, v106
	v_fma_f32 v112, v121, v106, v106
	v_fma_f32 v113, v123, v106, v106
	v_fmac_f32_e32 v106, v116, v106
	v_rcp_f32_e32 v107, v107
	v_rcp_f32_e32 v106, v106
	v_rcp_f32_e32 v108, v108
	v_rcp_f32_e32 v109, v109
	v_rcp_f32_e32 v110, v110
	v_rcp_f32_e32 v111, v111
	v_rcp_f32_e32 v112, v112
	v_rcp_f32_e32 v113, v113
	v_mul_f32_e32 v102, v102, v107
	v_mul_f32_e32 v101, v101, v106
	v_mul_f32_e32 v103, v103, v108
	v_mul_f32_e32 v104, v104, v109
	v_mul_f32_e32 v105, v105, v110
	v_mul_f32_e32 v107, v98, v111
	v_mul_f32_e32 v108, v99, v112
	v_mul_f32_e32 v109, v100, v113
	v_cvt_pk_bf16_f32 v98, v102, v103
	v_cvt_pk_bf16_f32 v99, v104, v105
	v_cvt_pk_bf16_f32 v100, v107, v108
	v_cvt_pk_bf16_f32 v101, v109, v101
	ds_read_b32 v102, v151 offset:128
	v_add_co_u32_e32 v114, vcc, 0x2c000, v152
	s_nop 1
	v_addc_co_u32_e32 v115, vcc, 0, v153, vcc
	global_store_dwordx4 v[114:115], v[98:101], off
	v_mul_f32_e32 v82, v90, v82
	v_mul_f32_e32 v86, v94, v86
	s_waitcnt lgkmcnt(0)
	v_mul_f32_e32 v100, 0xbfb8aa3b, v102
	v_mul_f32_e32 v101, v102, v102
	v_mul_f32_e32 v102, v94, v100
	v_mul_f32_e32 v103, v90, v100
	v_mul_f32_e32 v104, v95, v100
	v_mul_f32_e32 v105, v91, v100
	v_mul_f32_e32 v106, v96, v100
	v_mul_f32_e32 v107, v92, v100
	v_mul_f32_e32 v108, v97, v100
	v_mul_f32_e32 v100, v93, v100
	v_exp_f32_e32 v102, v102
	v_exp_f32_e32 v104, v104
	v_exp_f32_e32 v106, v106
	v_exp_f32_e32 v108, v108
	v_exp_f32_e32 v103, v103
	v_exp_f32_e32 v105, v105
	v_exp_f32_e32 v107, v107
	v_exp_f32_e32 v100, v100
	v_rcp_f32_e32 v90, v101
	v_mul_f32_e32 v87, v95, v87
	v_mul_f32_e32 v83, v91, v83
	v_mul_f32_e32 v88, v96, v88
	v_mul_f32_e32 v84, v92, v84
	v_mul_f32_e32 v89, v97, v89
	v_mul_f32_e32 v85, v93, v85
	v_fma_f32 v91, v102, v90, v90
	v_fma_f32 v92, v104, v90, v90
	v_fma_f32 v93, v106, v90, v90
	v_fma_f32 v94, v108, v90, v90
	v_fma_f32 v95, v103, v90, v90
	v_fma_f32 v96, v105, v90, v90
	v_fma_f32 v97, v107, v90, v90
	v_fmac_f32_e32 v90, v100, v90
	v_rcp_f32_e32 v91, v91
	v_rcp_f32_e32 v90, v90
	v_rcp_f32_e32 v92, v92
	v_rcp_f32_e32 v93, v93
	v_rcp_f32_e32 v94, v94
	v_rcp_f32_e32 v95, v95
	v_rcp_f32_e32 v96, v96
	v_rcp_f32_e32 v97, v97
	v_mul_f32_e32 v86, v86, v91
	v_mul_f32_e32 v85, v85, v90
	v_mul_f32_e32 v87, v87, v92
	v_mul_f32_e32 v88, v88, v93
	v_mul_f32_e32 v89, v89, v94
	v_mul_f32_e32 v91, v82, v95
	v_mul_f32_e32 v92, v83, v96
	v_mul_f32_e32 v93, v84, v97
	v_cvt_pk_bf16_f32 v82, v86, v87
	v_cvt_pk_bf16_f32 v83, v88, v89
	v_cvt_pk_bf16_f32 v84, v91, v92
	v_cvt_pk_bf16_f32 v85, v93, v85
	ds_read_b32 v86, v151 offset:192
	v_add_co_u32_e32 v98, vcc, 0x58000, v152
	s_nop 1
	v_addc_co_u32_e32 v99, vcc, 0, v153, vcc
	global_store_dwordx4 v[98:99], v[82:85], off
	v_mul_f32_e32 v66, v74, v66
	v_mul_f32_e32 v70, v78, v70
	s_waitcnt lgkmcnt(0)
	v_mul_f32_e32 v84, 0xbfb8aa3b, v86
	v_mul_f32_e32 v85, v86, v86
	v_mul_f32_e32 v86, v78, v84
	v_mul_f32_e32 v87, v74, v84
	v_mul_f32_e32 v88, v79, v84
	v_mul_f32_e32 v89, v75, v84
	v_mul_f32_e32 v90, v80, v84
	v_mul_f32_e32 v91, v76, v84
	v_mul_f32_e32 v92, v81, v84
	v_mul_f32_e32 v84, v77, v84
	v_exp_f32_e32 v86, v86
	v_exp_f32_e32 v88, v88
	v_exp_f32_e32 v90, v90
	v_exp_f32_e32 v92, v92
	v_exp_f32_e32 v87, v87
	v_exp_f32_e32 v89, v89
	v_exp_f32_e32 v91, v91
	v_exp_f32_e32 v84, v84
	v_rcp_f32_e32 v74, v85
	v_mul_f32_e32 v71, v79, v71
	v_mul_f32_e32 v67, v75, v67
	v_mul_f32_e32 v72, v80, v72
	v_mul_f32_e32 v68, v76, v68
	v_mul_f32_e32 v73, v81, v73
	v_mul_f32_e32 v69, v77, v69
	v_fma_f32 v75, v86, v74, v74
	v_fma_f32 v76, v88, v74, v74
	v_fma_f32 v77, v90, v74, v74
	v_fma_f32 v78, v92, v74, v74
	v_fma_f32 v79, v87, v74, v74
	v_fma_f32 v80, v89, v74, v74
	v_fma_f32 v81, v91, v74, v74
	v_fmac_f32_e32 v74, v84, v74
	v_rcp_f32_e32 v75, v75
	v_rcp_f32_e32 v74, v74
	v_rcp_f32_e32 v76, v76
	v_rcp_f32_e32 v77, v77
	v_rcp_f32_e32 v78, v78
	v_rcp_f32_e32 v79, v79
	v_rcp_f32_e32 v80, v80
	v_rcp_f32_e32 v81, v81
	v_mul_f32_e32 v70, v70, v75
	v_mul_f32_e32 v69, v69, v74
	v_mul_f32_e32 v71, v71, v76
	v_mul_f32_e32 v72, v72, v77
	v_mul_f32_e32 v73, v73, v78
	v_mul_f32_e32 v75, v66, v79
	v_mul_f32_e32 v76, v67, v80
	v_mul_f32_e32 v77, v68, v81
	v_cvt_pk_bf16_f32 v66, v70, v71
	v_cvt_pk_bf16_f32 v67, v72, v73
	v_cvt_pk_bf16_f32 v68, v75, v76
	v_cvt_pk_bf16_f32 v69, v77, v69
	ds_read_b32 v70, v151 offset:512
	v_add_co_u32_e32 v82, vcc, 0x84000, v152
	s_nop 1
	v_addc_co_u32_e32 v83, vcc, 0, v153, vcc
	global_store_dwordx4 v[82:83], v[66:69], off
	v_mul_f32_e32 v50, v58, v50
	v_mul_f32_e32 v54, v62, v54
	s_waitcnt lgkmcnt(0)
	v_mul_f32_e32 v68, 0xbfb8aa3b, v70
	v_mul_f32_e32 v69, v70, v70
	v_mul_f32_e32 v70, v62, v68
	v_mul_f32_e32 v71, v58, v68
	v_mul_f32_e32 v72, v63, v68
	v_mul_f32_e32 v73, v59, v68
	v_mul_f32_e32 v74, v64, v68
	v_mul_f32_e32 v75, v60, v68
	v_mul_f32_e32 v76, v65, v68
	v_mul_f32_e32 v68, v61, v68
	v_exp_f32_e32 v70, v70
	v_exp_f32_e32 v72, v72
	v_exp_f32_e32 v74, v74
	v_exp_f32_e32 v76, v76
	v_exp_f32_e32 v71, v71
	v_exp_f32_e32 v73, v73
	v_exp_f32_e32 v75, v75
	v_exp_f32_e32 v68, v68
	v_rcp_f32_e32 v58, v69
	v_mul_f32_e32 v55, v63, v55
	v_mul_f32_e32 v51, v59, v51
	v_mul_f32_e32 v56, v64, v56
	v_mul_f32_e32 v52, v60, v52
	v_mul_f32_e32 v57, v65, v57
	v_mul_f32_e32 v53, v61, v53
	v_fma_f32 v59, v70, v58, v58
	v_fma_f32 v60, v72, v58, v58
	v_fma_f32 v61, v74, v58, v58
	v_fma_f32 v62, v76, v58, v58
	v_fma_f32 v63, v71, v58, v58
	v_fma_f32 v64, v73, v58, v58
	v_fma_f32 v65, v75, v58, v58
	v_fmac_f32_e32 v58, v68, v58
	v_rcp_f32_e32 v59, v59
	v_rcp_f32_e32 v58, v58
	v_rcp_f32_e32 v60, v60
	v_rcp_f32_e32 v61, v61
	v_rcp_f32_e32 v62, v62
	v_rcp_f32_e32 v63, v63
	v_rcp_f32_e32 v64, v64
	v_rcp_f32_e32 v65, v65
	v_mul_f32_e32 v54, v54, v59
	v_mul_f32_e32 v53, v53, v58
	v_mul_f32_e32 v55, v55, v60
	v_mul_f32_e32 v56, v56, v61
	v_mul_f32_e32 v57, v57, v62
	v_mul_f32_e32 v59, v50, v63
	v_mul_f32_e32 v60, v51, v64
	v_mul_f32_e32 v61, v52, v65
	v_cvt_pk_bf16_f32 v50, v54, v55
	v_cvt_pk_bf16_f32 v51, v56, v57
	v_cvt_pk_bf16_f32 v52, v59, v60
	v_cvt_pk_bf16_f32 v53, v61, v53
	ds_read_b32 v54, v151 offset:576
	v_add_co_u32_e32 v66, vcc, 0x160000, v152
	s_nop 1
	v_addc_co_u32_e32 v67, vcc, 0, v153, vcc
	global_store_dwordx4 v[66:67], v[50:53], off
	v_mul_f32_e32 v34, v42, v34
	v_mul_f32_e32 v38, v46, v38
	s_waitcnt lgkmcnt(0)
	v_mul_f32_e32 v52, 0xbfb8aa3b, v54
	v_mul_f32_e32 v53, v54, v54
	v_mul_f32_e32 v54, v46, v52
	v_mul_f32_e32 v55, v42, v52
	v_mul_f32_e32 v56, v47, v52
	v_mul_f32_e32 v57, v43, v52
	v_mul_f32_e32 v58, v48, v52
	v_mul_f32_e32 v59, v44, v52
	v_mul_f32_e32 v60, v49, v52
	v_mul_f32_e32 v52, v45, v52
	v_exp_f32_e32 v54, v54
	v_exp_f32_e32 v56, v56
	v_exp_f32_e32 v58, v58
	v_exp_f32_e32 v60, v60
	v_exp_f32_e32 v55, v55
	v_exp_f32_e32 v57, v57
	v_exp_f32_e32 v59, v59
	v_exp_f32_e32 v52, v52
	v_rcp_f32_e32 v42, v53
	v_mul_f32_e32 v39, v47, v39
	v_mul_f32_e32 v35, v43, v35
	v_mul_f32_e32 v40, v48, v40
	v_mul_f32_e32 v36, v44, v36
	v_mul_f32_e32 v41, v49, v41
	v_mul_f32_e32 v37, v45, v37
	v_fma_f32 v43, v54, v42, v42
	v_fma_f32 v44, v56, v42, v42
	v_fma_f32 v45, v58, v42, v42
	v_fma_f32 v46, v60, v42, v42
	v_fma_f32 v47, v55, v42, v42
	v_fma_f32 v48, v57, v42, v42
	v_fma_f32 v49, v59, v42, v42
	v_fmac_f32_e32 v42, v52, v42
	v_rcp_f32_e32 v43, v43
	v_rcp_f32_e32 v42, v42
	v_rcp_f32_e32 v44, v44
	v_rcp_f32_e32 v45, v45
	v_rcp_f32_e32 v46, v46
	v_rcp_f32_e32 v47, v47
	v_rcp_f32_e32 v48, v48
	v_rcp_f32_e32 v49, v49
	v_mul_f32_e32 v38, v38, v43
	v_mul_f32_e32 v37, v37, v42
	v_mul_f32_e32 v39, v39, v44
	v_mul_f32_e32 v40, v40, v45
	v_mul_f32_e32 v41, v41, v46
	v_mul_f32_e32 v43, v34, v47
	v_mul_f32_e32 v44, v35, v48
	v_mul_f32_e32 v45, v36, v49
	v_cvt_pk_bf16_f32 v34, v38, v39
	v_cvt_pk_bf16_f32 v35, v40, v41
	v_cvt_pk_bf16_f32 v36, v43, v44
	v_cvt_pk_bf16_f32 v37, v45, v37
	ds_read_b32 v38, v151 offset:640
	v_add_co_u32_e32 v50, vcc, 0x18c000, v152
	s_nop 1
	v_addc_co_u32_e32 v51, vcc, 0, v153, vcc
	global_store_dwordx4 v[50:51], v[34:37], off
	v_mul_f32_e32 v18, v26, v18
	v_mul_f32_e32 v22, v30, v22
	s_waitcnt lgkmcnt(0)
	v_mul_f32_e32 v36, 0xbfb8aa3b, v38
	v_mul_f32_e32 v37, v38, v38
	v_mul_f32_e32 v38, v30, v36
	v_mul_f32_e32 v39, v26, v36
	v_mul_f32_e32 v40, v31, v36
	v_mul_f32_e32 v41, v27, v36
	v_mul_f32_e32 v42, v32, v36
	v_mul_f32_e32 v43, v28, v36
	v_mul_f32_e32 v44, v33, v36
	v_mul_f32_e32 v36, v29, v36
	v_exp_f32_e32 v38, v38
	v_exp_f32_e32 v40, v40
	v_exp_f32_e32 v42, v42
	v_exp_f32_e32 v44, v44
	v_exp_f32_e32 v39, v39
	v_exp_f32_e32 v41, v41
	v_exp_f32_e32 v43, v43
	v_exp_f32_e32 v36, v36
	v_rcp_f32_e32 v26, v37
	v_mul_f32_e32 v23, v31, v23
	v_mul_f32_e32 v19, v27, v19
	v_mul_f32_e32 v24, v32, v24
	v_mul_f32_e32 v20, v28, v20
	v_mul_f32_e32 v25, v33, v25
	v_mul_f32_e32 v21, v29, v21
	v_fma_f32 v27, v38, v26, v26
	v_fma_f32 v28, v40, v26, v26
	v_fma_f32 v29, v42, v26, v26
	v_fma_f32 v30, v44, v26, v26
	v_fma_f32 v31, v39, v26, v26
	v_fma_f32 v32, v41, v26, v26
	v_fma_f32 v33, v43, v26, v26
	v_fmac_f32_e32 v26, v36, v26
	v_rcp_f32_e32 v27, v27
	v_rcp_f32_e32 v26, v26
	v_rcp_f32_e32 v28, v28
	v_rcp_f32_e32 v29, v29
	v_rcp_f32_e32 v30, v30
	v_rcp_f32_e32 v31, v31
	v_rcp_f32_e32 v32, v32
	v_rcp_f32_e32 v33, v33
	v_mul_f32_e32 v22, v22, v27
	v_mul_f32_e32 v21, v21, v26
	v_mul_f32_e32 v23, v23, v28
	v_mul_f32_e32 v24, v24, v29
	v_mul_f32_e32 v25, v25, v30
	v_mul_f32_e32 v27, v18, v31
	v_mul_f32_e32 v28, v19, v32
	v_mul_f32_e32 v29, v20, v33
	v_cvt_pk_bf16_f32 v18, v22, v23
	v_cvt_pk_bf16_f32 v19, v24, v25
	v_cvt_pk_bf16_f32 v20, v27, v28
	v_cvt_pk_bf16_f32 v21, v29, v21
	ds_read_b32 v22, v151 offset:704
	v_add_co_u32_e32 v34, vcc, 0x1b8000, v152
	s_nop 1
	v_addc_co_u32_e32 v35, vcc, 0, v153, vcc
	global_store_dwordx4 v[34:35], v[18:21], off
	v_mul_f32_e32 v2, v10, v2
	v_mul_f32_e32 v6, v14, v6
	s_waitcnt lgkmcnt(0)
	v_mul_f32_e32 v20, 0xbfb8aa3b, v22
	v_mul_f32_e32 v21, v22, v22
	v_mul_f32_e32 v22, v14, v20
	v_mul_f32_e32 v23, v10, v20
	v_mul_f32_e32 v24, v15, v20
	v_mul_f32_e32 v25, v11, v20
	v_mul_f32_e32 v26, v16, v20
	v_mul_f32_e32 v27, v12, v20
	v_mul_f32_e32 v28, v17, v20
	v_mul_f32_e32 v20, v13, v20
	v_exp_f32_e32 v22, v22
	v_exp_f32_e32 v24, v24
	v_exp_f32_e32 v26, v26
	v_exp_f32_e32 v28, v28
	v_exp_f32_e32 v23, v23
	v_exp_f32_e32 v25, v25
	v_exp_f32_e32 v27, v27
	v_exp_f32_e32 v20, v20
	v_rcp_f32_e32 v10, v21
	v_mul_f32_e32 v7, v15, v7
	v_mul_f32_e32 v3, v11, v3
	v_mul_f32_e32 v8, v16, v8
	v_mul_f32_e32 v4, v12, v4
	v_mul_f32_e32 v9, v17, v9
	v_mul_f32_e32 v5, v13, v5
	v_fma_f32 v11, v22, v10, v10
	v_fma_f32 v12, v24, v10, v10
	v_fma_f32 v13, v26, v10, v10
	v_fma_f32 v14, v28, v10, v10
	v_fma_f32 v15, v23, v10, v10
	v_fma_f32 v16, v25, v10, v10
	v_fma_f32 v17, v27, v10, v10
	v_fmac_f32_e32 v10, v20, v10
	v_rcp_f32_e32 v10, v10
	v_rcp_f32_e32 v11, v11
	v_rcp_f32_e32 v12, v12
	v_rcp_f32_e32 v13, v13
	v_rcp_f32_e32 v14, v14
	v_rcp_f32_e32 v15, v15
	v_rcp_f32_e32 v16, v16
	v_rcp_f32_e32 v17, v17
	v_add_co_u32_e32 v18, vcc, 0x1e4000, v152
	s_nop 1
	v_addc_co_u32_e32 v19, vcc, 0, v153, vcc
	v_mul_f32_e32 v5, v5, v10
	s_andn2_b64 vcc, exec, s[22:23]
	s_mov_b64 s[22:23], -1
	v_mul_f32_e32 v6, v6, v11
	v_mul_f32_e32 v7, v7, v12
	v_mul_f32_e32 v8, v8, v13
	v_mul_f32_e32 v9, v9, v14
	v_mul_f32_e32 v11, v2, v15
	v_mul_f32_e32 v12, v3, v16
	v_mul_f32_e32 v13, v4, v17
	v_cvt_pk_bf16_f32 v2, v6, v7
	v_cvt_pk_bf16_f32 v3, v8, v9
	v_cvt_pk_bf16_f32 v4, v11, v12
	v_cvt_pk_bf16_f32 v5, v13, v5
	global_store_dwordx4 v[18:19], v[2:5], off
	s_cbranch_vccnz .LBB0_110
	s_andn2_b64 vcc, exec, s[12:13]
	s_cbranch_vccnz .LBB0_121
	s_lshl_b32 s21, s47, 10
	s_and_b32 s21, s21, 0x400
	s_add_i32 m0, s45, s21
	s_ashr_i32 s21, s20, 31
	s_lshl_b64 s[22:23], s[20:21], 10
	v_lshl_add_u64 v[2:3], v[130:131], 0, s[22:23]
	global_load_lds_dwordx4 v[2:3], off

.LBB0_707:
	s_lshl_b32 s53, s53, 10
	s_and_b32 s53, s53, 0x400
	v_add_u32_e32 v150, s53, v142
	ds_read_b32 v151, v150
	v_mul_f32_e32 v114, v122, v114
	v_mul_f32_e32 v118, v126, v118
	v_mul_f32_e32 v119, v127, v119
	v_mul_f32_e32 v115, v123, v115
	s_waitcnt lgkmcnt(0)
	v_mul_f32_e32 v152, 0xbfb8aa3b, v151
	v_mul_f32_e32 v151, v151, v151
	v_mul_f32_e32 v153, v126, v152
	v_mul_f32_e32 v154, v122, v152
	v_mul_f32_e32 v155, v127, v152
	v_mul_f32_e32 v156, v123, v152
	v_mul_f32_e32 v157, v128, v152
	v_mul_f32_e32 v158, v124, v152
	v_mul_f32_e32 v159, v129, v152
	v_mul_f32_e32 v152, v125, v152
	v_exp_f32_e32 v153, v153
	v_exp_f32_e32 v155, v155
	v_exp_f32_e32 v157, v157
	v_exp_f32_e32 v159, v159
	v_exp_f32_e32 v154, v154
	v_exp_f32_e32 v156, v156
	v_exp_f32_e32 v158, v158
	v_exp_f32_e32 v152, v152
	v_rcp_f32_e32 v122, v151
	v_mul_f32_e32 v120, v128, v120
	v_mul_f32_e32 v116, v124, v116
	v_mul_f32_e32 v121, v129, v121
	v_mul_f32_e32 v117, v125, v117
	v_fma_f32 v123, v153, v122, v122
	v_fma_f32 v124, v155, v122, v122
	v_fma_f32 v125, v157, v122, v122
	v_fma_f32 v126, v159, v122, v122
	v_fma_f32 v127, v154, v122, v122
	v_fma_f32 v128, v156, v122, v122
	v_fma_f32 v129, v158, v122, v122
	v_fmac_f32_e32 v122, v152, v122
	v_rcp_f32_e32 v123, v123
	v_rcp_f32_e32 v122, v122
	v_rcp_f32_e32 v124, v124
	v_rcp_f32_e32 v125, v125
	v_rcp_f32_e32 v126, v126
	v_rcp_f32_e32 v127, v127
	v_rcp_f32_e32 v128, v128
	v_rcp_f32_e32 v129, v129
	v_mul_f32_e32 v118, v118, v123
	v_mul_f32_e32 v117, v117, v122
	v_mul_f32_e32 v119, v119, v124
	v_mul_f32_e32 v120, v120, v125
	v_mul_f32_e32 v121, v121, v126
	v_mul_f32_e32 v123, v114, v127
	v_mul_f32_e32 v124, v115, v128
	v_mul_f32_e32 v125, v116, v129
	v_cvt_pk_bf16_f32 v114, v118, v119
	v_cvt_pk_bf16_f32 v115, v120, v121
	v_cvt_pk_bf16_f32 v116, v123, v124
	v_cvt_pk_bf16_f32 v117, v125, v117
	ds_read_b32 v118, v150 offset:64
	v_lshl_or_b32 v134, s21, 7, v143
	v_lshl_add_u32 v147, s24, 8, v140
	v_ashrrev_i32_e32 v135, 31, v134
	v_mov_b64_e32 v[132:133], s[0:1]
	s_movk_i32 s21, 0x2c00
	v_mad_i64_i32 v[148:149], s[54:55], v147, s21, v[132:133]
	v_lshlrev_b64 v[134:135], 1, v[134:135]
	v_lshl_add_u64 v[148:149], v[148:149], 0, v[134:135]
	global_store_dwordx4 v[148:149], v[114:117], off
	v_mul_f32_e32 v98, v106, v98
	v_mul_f32_e32 v102, v110, v102
	s_waitcnt lgkmcnt(0)
	v_mul_f32_e32 v116, 0xbfb8aa3b, v118
	v_mul_f32_e32 v117, v118, v118
	v_mul_f32_e32 v118, v110, v116
	v_mul_f32_e32 v119, v106, v116
	v_mul_f32_e32 v120, v111, v116
	v_mul_f32_e32 v121, v107, v116
	v_mul_f32_e32 v122, v112, v116
	v_mul_f32_e32 v123, v108, v116
	v_mul_f32_e32 v124, v113, v116
	v_mul_f32_e32 v116, v109, v116
	v_exp_f32_e32 v118, v118
	v_exp_f32_e32 v120, v120
	v_exp_f32_e32 v122, v122
	v_exp_f32_e32 v124, v124
	v_exp_f32_e32 v119, v119
	v_exp_f32_e32 v121, v121
	v_exp_f32_e32 v123, v123
	v_exp_f32_e32 v116, v116
	v_rcp_f32_e32 v106, v117
	v_mul_f32_e32 v103, v111, v103
	v_mul_f32_e32 v99, v107, v99
	v_mul_f32_e32 v104, v112, v104
	v_mul_f32_e32 v100, v108, v100
	v_mul_f32_e32 v105, v113, v105
	v_mul_f32_e32 v101, v109, v101
	v_fma_f32 v107, v118, v106, v106
	v_fma_f32 v108, v120, v106, v106
	v_fma_f32 v109, v122, v106, v106
	v_fma_f32 v110, v124, v106, v106
	v_fma_f32 v111, v119, v106, v106
	v_fma_f32 v112, v121, v106, v106
	v_fma_f32 v113, v123, v106, v106
	v_fmac_f32_e32 v106, v116, v106
	v_rcp_f32_e32 v107, v107
	v_rcp_f32_e32 v106, v106
	v_rcp_f32_e32 v108, v108
	v_rcp_f32_e32 v109, v109
	v_rcp_f32_e32 v110, v110
	v_rcp_f32_e32 v111, v111
	v_rcp_f32_e32 v112, v112
	v_rcp_f32_e32 v113, v113
	v_mul_f32_e32 v102, v102, v107
	v_mul_f32_e32 v101, v101, v106
	v_mul_f32_e32 v103, v103, v108
	v_mul_f32_e32 v104, v104, v109
	v_mul_f32_e32 v105, v105, v110
	v_mul_f32_e32 v107, v98, v111
	v_mul_f32_e32 v108, v99, v112
	v_mul_f32_e32 v109, v100, v113
	v_cvt_pk_bf16_f32 v98, v102, v103
	v_cvt_pk_bf16_f32 v99, v104, v105
	v_cvt_pk_bf16_f32 v100, v107, v108
	v_cvt_pk_bf16_f32 v101, v109, v101
	ds_read_b32 v102, v150 offset:128
	v_add_co_u32_e32 v114, vcc, 0x2c000, v148
	s_nop 1
	v_addc_co_u32_e32 v115, vcc, 0, v149, vcc
	global_store_dwordx4 v[114:115], v[98:101], off
	v_mul_f32_e32 v82, v90, v82
	v_mul_f32_e32 v86, v94, v86
	s_waitcnt lgkmcnt(0)
	v_mul_f32_e32 v100, 0xbfb8aa3b, v102
	v_mul_f32_e32 v101, v102, v102
	v_mul_f32_e32 v102, v94, v100
	v_mul_f32_e32 v103, v90, v100
	v_mul_f32_e32 v104, v95, v100
	v_mul_f32_e32 v105, v91, v100
	v_mul_f32_e32 v106, v96, v100
	v_mul_f32_e32 v107, v92, v100
	v_mul_f32_e32 v108, v97, v100
	v_mul_f32_e32 v100, v93, v100
	v_exp_f32_e32 v102, v102
	v_exp_f32_e32 v104, v104
	v_exp_f32_e32 v106, v106
	v_exp_f32_e32 v108, v108
	v_exp_f32_e32 v103, v103
	v_exp_f32_e32 v105, v105
	v_exp_f32_e32 v107, v107
	v_exp_f32_e32 v100, v100
	v_rcp_f32_e32 v90, v101
	v_mul_f32_e32 v87, v95, v87
	v_mul_f32_e32 v83, v91, v83
	v_mul_f32_e32 v88, v96, v88
	v_mul_f32_e32 v84, v92, v84
	v_mul_f32_e32 v89, v97, v89
	v_mul_f32_e32 v85, v93, v85
	v_fma_f32 v91, v102, v90, v90
	v_fma_f32 v92, v104, v90, v90
	v_fma_f32 v93, v106, v90, v90
	v_fma_f32 v94, v108, v90, v90
	v_fma_f32 v95, v103, v90, v90
	v_fma_f32 v96, v105, v90, v90
	v_fma_f32 v97, v107, v90, v90
	v_fmac_f32_e32 v90, v100, v90
	v_rcp_f32_e32 v91, v91
	v_rcp_f32_e32 v90, v90
	v_rcp_f32_e32 v92, v92
	v_rcp_f32_e32 v93, v93
	v_rcp_f32_e32 v94, v94
	v_rcp_f32_e32 v95, v95
	v_rcp_f32_e32 v96, v96
	v_rcp_f32_e32 v97, v97
	v_mul_f32_e32 v86, v86, v91
	v_mul_f32_e32 v85, v85, v90
	v_mul_f32_e32 v87, v87, v92
	v_mul_f32_e32 v88, v88, v93
	v_mul_f32_e32 v89, v89, v94
	v_mul_f32_e32 v91, v82, v95
	v_mul_f32_e32 v92, v83, v96
	v_mul_f32_e32 v93, v84, v97
	v_cvt_pk_bf16_f32 v82, v86, v87
	v_cvt_pk_bf16_f32 v83, v88, v89
	v_cvt_pk_bf16_f32 v84, v91, v92
	v_cvt_pk_bf16_f32 v85, v93, v85
	ds_read_b32 v86, v150 offset:192
	v_add_co_u32_e32 v98, vcc, 0x58000, v148
	s_nop 1
	v_addc_co_u32_e32 v99, vcc, 0, v149, vcc
	global_store_dwordx4 v[98:99], v[82:85], off
	v_mul_f32_e32 v66, v74, v66
	v_mul_f32_e32 v70, v78, v70
	s_waitcnt lgkmcnt(0)
	v_mul_f32_e32 v84, 0xbfb8aa3b, v86
	v_mul_f32_e32 v85, v86, v86
	v_mul_f32_e32 v86, v78, v84
	v_mul_f32_e32 v87, v74, v84
	v_mul_f32_e32 v88, v79, v84
	v_mul_f32_e32 v89, v75, v84
	v_mul_f32_e32 v90, v80, v84
	v_mul_f32_e32 v91, v76, v84
	v_mul_f32_e32 v92, v81, v84
	v_mul_f32_e32 v84, v77, v84
	v_exp_f32_e32 v86, v86
	v_exp_f32_e32 v88, v88
	v_exp_f32_e32 v90, v90
	v_exp_f32_e32 v92, v92
	v_exp_f32_e32 v87, v87
	v_exp_f32_e32 v89, v89
	v_exp_f32_e32 v91, v91
	v_exp_f32_e32 v84, v84
	v_rcp_f32_e32 v74, v85
	v_mul_f32_e32 v71, v79, v71
	v_mul_f32_e32 v67, v75, v67
	v_mul_f32_e32 v72, v80, v72
	v_mul_f32_e32 v68, v76, v68
	v_mul_f32_e32 v73, v81, v73
	v_mul_f32_e32 v69, v77, v69
	v_fma_f32 v75, v86, v74, v74
	v_fma_f32 v76, v88, v74, v74
	v_fma_f32 v77, v90, v74, v74
	v_fma_f32 v78, v92, v74, v74
	v_fma_f32 v79, v87, v74, v74
	v_fma_f32 v80, v89, v74, v74
	v_fma_f32 v81, v91, v74, v74
	v_fmac_f32_e32 v74, v84, v74
	v_rcp_f32_e32 v75, v75
	v_rcp_f32_e32 v74, v74
	v_rcp_f32_e32 v76, v76
	v_rcp_f32_e32 v77, v77
	v_rcp_f32_e32 v78, v78
	v_rcp_f32_e32 v79, v79
	v_rcp_f32_e32 v80, v80
	v_rcp_f32_e32 v81, v81
	v_mul_f32_e32 v70, v70, v75
	v_mul_f32_e32 v69, v69, v74
	v_mul_f32_e32 v71, v71, v76
	v_mul_f32_e32 v72, v72, v77
	v_mul_f32_e32 v73, v73, v78
	v_mul_f32_e32 v75, v66, v79
	v_mul_f32_e32 v76, v67, v80
	v_mul_f32_e32 v77, v68, v81
	v_cvt_pk_bf16_f32 v66, v70, v71
	v_cvt_pk_bf16_f32 v67, v72, v73
	v_cvt_pk_bf16_f32 v68, v75, v76
	v_cvt_pk_bf16_f32 v69, v77, v69
	ds_read_b32 v70, v150 offset:512
	v_add_co_u32_e32 v82, vcc, 0x84000, v148
	s_nop 1
	v_addc_co_u32_e32 v83, vcc, 0, v149, vcc
	global_store_dwordx4 v[82:83], v[66:69], off
	v_mul_f32_e32 v50, v58, v50
	v_mul_f32_e32 v54, v62, v54
	s_waitcnt lgkmcnt(0)
	v_mul_f32_e32 v68, 0xbfb8aa3b, v70
	v_mul_f32_e32 v69, v70, v70
	v_mul_f32_e32 v70, v62, v68
	v_mul_f32_e32 v71, v58, v68
	v_mul_f32_e32 v72, v63, v68
	v_mul_f32_e32 v73, v59, v68
	v_mul_f32_e32 v74, v64, v68
	v_mul_f32_e32 v75, v60, v68
	v_mul_f32_e32 v76, v65, v68
	v_mul_f32_e32 v68, v61, v68
	v_exp_f32_e32 v70, v70
	v_exp_f32_e32 v72, v72
	v_exp_f32_e32 v74, v74
	v_exp_f32_e32 v76, v76
	v_exp_f32_e32 v71, v71
	v_exp_f32_e32 v73, v73
	v_exp_f32_e32 v75, v75
	v_exp_f32_e32 v68, v68
	v_rcp_f32_e32 v58, v69
	v_mul_f32_e32 v55, v63, v55
	v_mul_f32_e32 v51, v59, v51
	v_mul_f32_e32 v56, v64, v56
	v_mul_f32_e32 v52, v60, v52
	v_mul_f32_e32 v57, v65, v57
	v_mul_f32_e32 v53, v61, v53
	v_fma_f32 v59, v70, v58, v58
	v_fma_f32 v60, v72, v58, v58
	v_fma_f32 v61, v74, v58, v58
	v_fma_f32 v62, v76, v58, v58
	v_fma_f32 v63, v71, v58, v58
	v_fma_f32 v64, v73, v58, v58
	v_fma_f32 v65, v75, v58, v58
	v_fmac_f32_e32 v58, v68, v58
	v_rcp_f32_e32 v59, v59
	v_rcp_f32_e32 v58, v58
	v_rcp_f32_e32 v60, v60
	v_rcp_f32_e32 v61, v61
	v_rcp_f32_e32 v62, v62
	v_rcp_f32_e32 v63, v63
	v_rcp_f32_e32 v64, v64
	v_rcp_f32_e32 v65, v65
	v_mul_f32_e32 v54, v54, v59
	v_mul_f32_e32 v53, v53, v58
	v_mul_f32_e32 v55, v55, v60
	v_mul_f32_e32 v56, v56, v61
	v_mul_f32_e32 v57, v57, v62
	v_mul_f32_e32 v59, v50, v63
	v_mul_f32_e32 v60, v51, v64
	v_mul_f32_e32 v61, v52, v65
	v_cvt_pk_bf16_f32 v50, v54, v55
	v_cvt_pk_bf16_f32 v51, v56, v57
	v_cvt_pk_bf16_f32 v52, v59, v60
	v_cvt_pk_bf16_f32 v53, v61, v53
	ds_read_b32 v54, v150 offset:576
	v_add_co_u32_e32 v66, vcc, 0x160000, v148
	s_nop 1
	v_addc_co_u32_e32 v67, vcc, 0, v149, vcc
	global_store_dwordx4 v[66:67], v[50:53], off
	v_mul_f32_e32 v34, v42, v34
	v_mul_f32_e32 v38, v46, v38
	s_waitcnt lgkmcnt(0)
	v_mul_f32_e32 v52, 0xbfb8aa3b, v54
	v_mul_f32_e32 v53, v54, v54
	v_mul_f32_e32 v54, v46, v52
	v_mul_f32_e32 v55, v42, v52
	v_mul_f32_e32 v56, v47, v52
	v_mul_f32_e32 v57, v43, v52
	v_mul_f32_e32 v58, v48, v52
	v_mul_f32_e32 v59, v44, v52
	v_mul_f32_e32 v60, v49, v52
	v_mul_f32_e32 v52, v45, v52
	v_exp_f32_e32 v54, v54
	v_exp_f32_e32 v56, v56
	v_exp_f32_e32 v58, v58
	v_exp_f32_e32 v60, v60
	v_exp_f32_e32 v55, v55
	v_exp_f32_e32 v57, v57
	v_exp_f32_e32 v59, v59
	v_exp_f32_e32 v52, v52
	v_rcp_f32_e32 v42, v53
	v_mul_f32_e32 v39, v47, v39
	v_mul_f32_e32 v35, v43, v35
	v_mul_f32_e32 v40, v48, v40
	v_mul_f32_e32 v36, v44, v36
	v_mul_f32_e32 v41, v49, v41
	v_mul_f32_e32 v37, v45, v37
	v_fma_f32 v43, v54, v42, v42
	v_fma_f32 v44, v56, v42, v42
	v_fma_f32 v45, v58, v42, v42
	v_fma_f32 v46, v60, v42, v42
	v_fma_f32 v47, v55, v42, v42
	v_fma_f32 v48, v57, v42, v42
	v_fma_f32 v49, v59, v42, v42
	v_fmac_f32_e32 v42, v52, v42
	v_rcp_f32_e32 v43, v43
	v_rcp_f32_e32 v42, v42
	v_rcp_f32_e32 v44, v44
	v_rcp_f32_e32 v45, v45
	v_rcp_f32_e32 v46, v46
	v_rcp_f32_e32 v47, v47
	v_rcp_f32_e32 v48, v48
	v_rcp_f32_e32 v49, v49
	v_mul_f32_e32 v38, v38, v43
	v_mul_f32_e32 v37, v37, v42
	v_mul_f32_e32 v39, v39, v44
	v_mul_f32_e32 v40, v40, v45
	v_mul_f32_e32 v41, v41, v46
	v_mul_f32_e32 v43, v34, v47
	v_mul_f32_e32 v44, v35, v48
	v_mul_f32_e32 v45, v36, v49
	v_cvt_pk_bf16_f32 v34, v38, v39
	v_cvt_pk_bf16_f32 v35, v40, v41
	v_cvt_pk_bf16_f32 v36, v43, v44
	v_cvt_pk_bf16_f32 v37, v45, v37
	ds_read_b32 v38, v150 offset:640
	v_add_co_u32_e32 v50, vcc, 0x18c000, v148
	s_nop 1
	v_addc_co_u32_e32 v51, vcc, 0, v149, vcc
	global_store_dwordx4 v[50:51], v[34:37], off
	v_mul_f32_e32 v18, v26, v18
	v_mul_f32_e32 v22, v30, v22
	s_waitcnt lgkmcnt(0)
	v_mul_f32_e32 v36, 0xbfb8aa3b, v38
	v_mul_f32_e32 v37, v38, v38
	v_mul_f32_e32 v38, v30, v36
	v_mul_f32_e32 v39, v26, v36
	v_mul_f32_e32 v40, v31, v36
	v_mul_f32_e32 v41, v27, v36
	v_mul_f32_e32 v42, v32, v36
	v_mul_f32_e32 v43, v28, v36
	v_mul_f32_e32 v44, v33, v36
	v_mul_f32_e32 v36, v29, v36
	v_exp_f32_e32 v38, v38
	v_exp_f32_e32 v40, v40
	v_exp_f32_e32 v42, v42
	v_exp_f32_e32 v44, v44
	v_exp_f32_e32 v39, v39
	v_exp_f32_e32 v41, v41
	v_exp_f32_e32 v43, v43
	v_exp_f32_e32 v36, v36
	v_rcp_f32_e32 v26, v37
	v_mul_f32_e32 v23, v31, v23
	v_mul_f32_e32 v19, v27, v19
	v_mul_f32_e32 v24, v32, v24
	v_mul_f32_e32 v20, v28, v20
	v_mul_f32_e32 v25, v33, v25
	v_mul_f32_e32 v21, v29, v21
	v_fma_f32 v27, v38, v26, v26
	v_fma_f32 v28, v40, v26, v26
	v_fma_f32 v29, v42, v26, v26
	v_fma_f32 v30, v44, v26, v26
	v_fma_f32 v31, v39, v26, v26
	v_fma_f32 v32, v41, v26, v26
	v_fma_f32 v33, v43, v26, v26
	v_fmac_f32_e32 v26, v36, v26
	v_rcp_f32_e32 v27, v27
	v_rcp_f32_e32 v26, v26
	v_rcp_f32_e32 v28, v28
	v_rcp_f32_e32 v29, v29
	v_rcp_f32_e32 v30, v30
	v_rcp_f32_e32 v31, v31
	v_rcp_f32_e32 v32, v32
	v_rcp_f32_e32 v33, v33
	v_mul_f32_e32 v22, v22, v27
	v_mul_f32_e32 v21, v21, v26
	v_mul_f32_e32 v23, v23, v28
	v_mul_f32_e32 v24, v24, v29
	v_mul_f32_e32 v25, v25, v30
	v_mul_f32_e32 v27, v18, v31
	v_mul_f32_e32 v28, v19, v32
	v_mul_f32_e32 v29, v20, v33
	v_cvt_pk_bf16_f32 v18, v22, v23
	v_cvt_pk_bf16_f32 v19, v24, v25
	v_cvt_pk_bf16_f32 v20, v27, v28
	v_cvt_pk_bf16_f32 v21, v29, v21
	ds_read_b32 v22, v150 offset:704
	v_add_co_u32_e32 v34, vcc, 0x1b8000, v148
	s_nop 1
	v_addc_co_u32_e32 v35, vcc, 0, v149, vcc
	global_store_dwordx4 v[34:35], v[18:21], off
	v_mul_f32_e32 v2, v10, v2
	v_mul_f32_e32 v6, v14, v6
	s_waitcnt lgkmcnt(0)
	v_mul_f32_e32 v20, 0xbfb8aa3b, v22
	v_mul_f32_e32 v21, v22, v22
	v_mul_f32_e32 v22, v14, v20
	v_mul_f32_e32 v23, v10, v20
	v_mul_f32_e32 v24, v15, v20
	v_mul_f32_e32 v25, v11, v20
	v_mul_f32_e32 v26, v16, v20
	v_mul_f32_e32 v27, v12, v20
	v_mul_f32_e32 v28, v17, v20
	v_mul_f32_e32 v20, v13, v20
	v_exp_f32_e32 v22, v22
	v_exp_f32_e32 v24, v24
	v_exp_f32_e32 v26, v26
	v_exp_f32_e32 v28, v28
	v_exp_f32_e32 v23, v23
	v_exp_f32_e32 v25, v25
	v_exp_f32_e32 v27, v27
	v_exp_f32_e32 v20, v20
	v_rcp_f32_e32 v10, v21
	v_mul_f32_e32 v7, v15, v7
	v_mul_f32_e32 v3, v11, v3
	v_mul_f32_e32 v8, v16, v8
	v_mul_f32_e32 v4, v12, v4
	v_mul_f32_e32 v9, v17, v9
	v_mul_f32_e32 v5, v13, v5
	v_fma_f32 v11, v22, v10, v10
	v_fma_f32 v12, v24, v10, v10
	v_fma_f32 v13, v26, v10, v10
	v_fma_f32 v14, v28, v10, v10
	v_fma_f32 v15, v23, v10, v10
	v_fma_f32 v16, v25, v10, v10
	v_fma_f32 v17, v27, v10, v10
	v_fmac_f32_e32 v10, v20, v10
	v_rcp_f32_e32 v10, v10
	v_rcp_f32_e32 v11, v11
	v_rcp_f32_e32 v12, v12
	v_rcp_f32_e32 v13, v13
	v_rcp_f32_e32 v14, v14
	v_rcp_f32_e32 v15, v15
	v_rcp_f32_e32 v16, v16
	v_rcp_f32_e32 v17, v17
	v_add_co_u32_e32 v18, vcc, 0x1e4000, v148
	s_nop 1
	v_addc_co_u32_e32 v19, vcc, 0, v149, vcc
	v_mul_f32_e32 v5, v5, v10
	s_andn2_b64 vcc, exec, s[22:23]
	s_mov_b64 s[22:23], -1
	v_mul_f32_e32 v6, v6, v11
	v_mul_f32_e32 v7, v7, v12
	v_mul_f32_e32 v8, v8, v13
	v_mul_f32_e32 v9, v9, v14
	v_mul_f32_e32 v11, v2, v15
	v_mul_f32_e32 v12, v3, v16
	v_mul_f32_e32 v13, v4, v17
	v_cvt_pk_bf16_f32 v2, v6, v7
	v_cvt_pk_bf16_f32 v3, v8, v9
	v_cvt_pk_bf16_f32 v4, v11, v12
	v_cvt_pk_bf16_f32 v5, v13, v5
	global_store_dwordx4 v[18:19], v[2:5], off
	s_cbranch_vccnz .LBB0_699
	s_andn2_b64 vcc, exec, s[12:13]
	s_cbranch_vccnz .LBB0_710
	s_lshl_b32 s21, s51, 10
	s_and_b32 s21, s21, 0x400
	s_add_i32 m0, s49, s21
	s_ashr_i32 s21, s20, 31
	s_lshl_b64 s[22:23], s[20:21], 10
	v_lshl_add_u64 v[2:3], v[130:131], 0, s[22:23]
	global_load_lds_dwordx4 v[2:3], off
